# P8: bf16 normalised rows stored without write-through (their only reader, the P9 tile of the same row panel, runs on the same XCD)
# speedup vs baseline: 1.0094x; 1.0094x over previous
; __device__ __forceinline__ void xn2_rows(const bf16* __restrict__ hb, const float* __restrict__ g, bf16* __restrict__ outp, unsigned char* __restrict__ xq, float* __restrict__ xs, int gwave, int nwaves, int lane, int rend) {
;     ...
;         const v4u* xb = (const v4u*)(hb + (size_t)row * D) + lane;
;         float v[2][8]; float ss = 0.f;
; #pragma unroll
;         for (int j = 0; j < 2; ++j) { const v4u w = xb[64 * j]; const unsigned ww[4] = {w.x, w.y, w.z, w.w};
; #pragma unroll
;             for (int e = 0; e < 4; ++e) { v[j][2 * e] = __uint_as_float(ww[e] << 16); v[j][2 * e + 1] = __uint_as_float(ww[e] & 0xffff0000u); ss += v[j][2 * e] * v[j][2 * e] + v[j][2 * e + 1] * v[j][2 * e + 1]; } }
;         ss = wave_sum(ss);
;         const float r = rsqrtf(ss * (1.f / D) + EPS);
;         float y[2][8]; float mx = 0.f;
; #pragma unroll
;         for (int j = 0; j < 2; ++j) { const float4 g0 = ((const float4*)g)[2 * lane + 128 * j], g1 = ((const float4*)g)[2 * lane + 128 * j + 1]; const float gg[8] = {g0.x, g0.y, g0.z, g0.w, g1.x, g1.y, g1.z, g1.w};
; #pragma unroll
;             for (int e = 0; e < 8; ++e) { y[j][e] = v[j][e] * r * gg[e]; mx = fmaxf(mx, fabsf(y[j][e])); }
;             v4u ow; ow.x = pk2(y[j][0], y[j][1]); ow.y = pk2(y[j][2], y[j][3]); ow.z = pk2(y[j][4], y[j][5]); ow.w = pk2(y[j][6], y[j][7]);
;             __builtin_amdgcn_raw_buffer_store_b128(ow, rsO, (int)(((unsigned)row * D + 8u * (unsigned)lane + 512u * j) * 2u), 0, 16); }
;         mx = wave_max_dpp(mx);
;         const float sc = mx > 0.f ? mx * (1.f / 119.f) : 1.f, inv = 1.f / sc;
;         int sx = 0; unsigned W[4];
; #pragma unroll
;         for (int j = 0; j < 2; ++j) { unsigned wh = 0u, wl = 0u;
; #pragma unroll
;             for (int e = 0; e < 8; ++e) { const int q = (int)rintf(y[j][e] * inv); sx += q; const unsigned tq = (unsigned)(q + 8);
.Lp8_trip:
	s_waitcnt vmcnt(8)
	v_lshlrev_b32_e32 v34, 16, v84
	v_and_b32_e32 v35, 0xffff0000, v84
	v_lshlrev_b32_e32 v36, 16, v85
	v_and_b32_e32 v37, 0xffff0000, v85
	v_lshlrev_b32_e32 v38, 16, v86
	v_and_b32_e32 v39, 0xffff0000, v86
	v_lshlrev_b32_e32 v40, 16, v87
	v_and_b32_e32 v41, 0xffff0000, v87
	v_lshlrev_b32_e32 v42, 16, v88
	v_and_b32_e32 v43, 0xffff0000, v88
	v_lshlrev_b32_e32 v44, 16, v89
	v_and_b32_e32 v45, 0xffff0000, v89
	v_lshlrev_b32_e32 v46, 16, v90
	v_and_b32_e32 v47, 0xffff0000, v90
	v_lshlrev_b32_e32 v48, 16, v91
	v_and_b32_e32 v49, 0xffff0000, v91
	v_lshl_add_u64 v[148:149], v[148:149], 0, s[100:101]
	global_load_dwordx4 v[84:87], v[148:149], off
	global_load_dwordx4 v[88:91], v[148:149], off offset:1024
	v_pk_mul_f32 v[50:51], v[34:35], v[34:35]
	v_pk_fma_f32 v[50:51], v[36:37], v[36:37], v[50:51]
	v_pk_fma_f32 v[50:51], v[38:39], v[38:39], v[50:51]
	v_pk_fma_f32 v[50:51], v[40:41], v[40:41], v[50:51]
	v_pk_fma_f32 v[50:51], v[42:43], v[42:43], v[50:51]
	v_pk_fma_f32 v[50:51], v[44:45], v[44:45], v[50:51]
	v_pk_fma_f32 v[50:51], v[46:47], v[46:47], v[50:51]
	v_pk_fma_f32 v[50:51], v[48:49], v[48:49], v[50:51]
	v_add_f32_e32 v52, v50, v51
	s_nop 1
	v_add_f32_dpp v52, v52, v52 quad_perm:[1,0,3,2] row_mask:0xf bank_mask:0xf bound_ctrl:1
	s_nop 1
	v_add_f32_dpp v52, v52, v52 quad_perm:[2,3,0,1] row_mask:0xf bank_mask:0xf bound_ctrl:1
	s_nop 1
	v_add_f32_dpp v52, v52, v52 row_half_mirror row_mask:0xf bank_mask:0xf bound_ctrl:1
	s_nop 1
	v_add_f32_dpp v52, v52, v52 row_mirror row_mask:0xf bank_mask:0xf bound_ctrl:1
	s_nop 1
	v_readlane_b32 s28, v52, 16
	v_readlane_b32 s29, v52, 48
	v_readlane_b32 s24, v52, 0
	v_readlane_b32 s25, v52, 32
	s_nop 1
	v_mov_b32_e32 v52, s28
	v_mov_b32_e32 v53, s29
	v_pk_add_f32 v[52:53], s[24:25], v[52:53]
	s_nop 0
	v_add_f32_e32 v52, v52, v53
	v_fmamk_f32 v52, v52, 0x3a800000, v29
	v_rsq_f32_e32 v54, v52
	s_nop 0
	v_pk_mul_f32 v[56:57], v[54:55], v[34:35] op_sel_hi:[0,1]
	v_pk_mul_f32 v[164:165], v[6:7], v[56:57]
	v_pk_mul_f32 v[56:57], v[54:55], v[36:37] op_sel_hi:[0,1]
	v_pk_mul_f32 v[166:167], v[8:9], v[56:57]
	v_pk_mul_f32 v[56:57], v[54:55], v[38:39] op_sel_hi:[0,1]
	v_pk_mul_f32 v[168:169], v[2:3], v[56:57]
	v_pk_mul_f32 v[56:57], v[54:55], v[40:41] op_sel_hi:[0,1]
	v_pk_mul_f32 v[170:171], v[4:5], v[56:57]
	v_pk_mul_f32 v[56:57], v[54:55], v[42:43] op_sel_hi:[0,1]
	v_pk_mul_f32 v[172:173], v[14:15], v[56:57]
	v_pk_mul_f32 v[56:57], v[54:55], v[44:45] op_sel_hi:[0,1]
	v_pk_mul_f32 v[174:175], v[16:17], v[56:57]
	v_pk_mul_f32 v[56:57], v[54:55], v[46:47] op_sel_hi:[0,1]
	v_pk_mul_f32 v[176:177], v[10:11], v[56:57]
	v_pk_mul_f32 v[56:57], v[54:55], v[48:49] op_sel_hi:[0,1]
	v_pk_mul_f32 v[178:179], v[12:13], v[56:57]
	v_max3_f32 v58, |v164|, 0, |v165|
	v_max3_f32 v58, v58, |v166|, |v167|
	v_max3_f32 v58, v58, |v168|, |v169|
	v_max3_f32 v58, v58, |v170|, |v171|
	v_max3_f32 v58, v58, |v172|, |v173|
	v_max3_f32 v58, v58, |v174|, |v175|
	v_max3_f32 v58, v58, |v176|, |v177|
	v_max3_f32 v58, v58, |v178|, |v179|
	v_cvt_pk_bf16_f32 v62, v164, v165
	v_cvt_pk_bf16_f32 v63, v166, v167
	v_cvt_pk_bf16_f32 v64, v168, v169
	v_cvt_pk_bf16_f32 v65, v170, v171
	v_cvt_pk_bf16_f32 v66, v172, v173
	v_cvt_pk_bf16_f32 v67, v174, v175
	v_cvt_pk_bf16_f32 v68, v176, v177
	v_cvt_pk_bf16_f32 v69, v178, v179
	buffer_store_dwordx4 v[62:65], v210, s[12:15], 0 offen
	buffer_store_dwordx4 v[66:69], v210, s[12:15], 0 offen offset:1024
	v_add_u32_e32 v210, 0x4000, v210
	s_nop 1
	v_max_f32_dpp v58, v58, v58 quad_perm:[1,0,3,2] row_mask:0xf bank_mask:0xf
	s_nop 1
	v_max_f32_dpp v58, v58, v58 quad_perm:[2,3,0,1] row_mask:0xf bank_mask:0xf
	s_nop 1
	v_max_f32_dpp v58, v58, v58 row_half_mirror row_mask:0xf bank_mask:0xf
	s_nop 1
	v_max_f32_dpp v58, v58, v58 row_mirror row_mask:0xf bank_mask:0xf
	s_nop 1
	v_readlane_b32 s28, v58, 32
	v_readlane_b32 s29, v58, 48
	v_readlane_b32 s24, v58, 0
	v_readlane_b32 s25, v58, 16
	s_nop 1
	v_mov_b32_e32 v59, s29
	v_max_f32_e32 v59, s28, v59
	v_mov_b32_e32 v70, s25
	v_max3_f32 v59, s24, v70, v59
	v_mul_f32_e32 v70, 0x3c09ae41, v59
	v_cmp_lt_f32_e32 vcc, 0, v59
	s_nop 1
	v_cndmask_b32_e32 v59, 1.0, v70, vcc
	v_div_scale_f32 v70, s[24:25], v59, v59, 1.0
	v_rcp_f32_e32 v71, v70
	v_div_scale_f32 v72, vcc, 1.0, v59, 1.0
	v_fma_f32 v73, -v70, v71, 1.0
	v_fmac_f32_e32 v71, v73, v71
	v_mul_f32_e32 v73, v72, v71
	v_fma_f32 v74, -v70, v73, v72
	v_fmac_f32_e32 v73, v74, v71
	v_fma_f32 v70, -v70, v73, v72
	v_div_fmas_f32 v70, v70, v71, v73
	v_div_fixup_f32 v60, v70, v59, 1.0
	v_pk_mul_f32 v[56:57], v[60:61], v[164:165] op_sel_hi:[0,1]
	v_pk_add_f32 v[180:181], s[46:47], v[56:57]
	v_pk_mul_f32 v[56:57], v[60:61], v[166:167] op_sel_hi:[0,1]
	v_pk_add_f32 v[182:183], s[46:47], v[56:57]
	v_pk_mul_f32 v[56:57], v[60:61], v[168:169] op_sel_hi:[0,1]
	v_pk_add_f32 v[184:185], s[46:47], v[56:57]
	v_pk_mul_f32 v[56:57], v[60:61], v[170:171] op_sel_hi:[0,1]
	v_pk_add_f32 v[186:187], s[46:47], v[56:57]
	v_pk_mul_f32 v[56:57], v[60:61], v[172:173] op_sel_hi:[0,1]
	v_pk_add_f32 v[188:189], s[46:47], v[56:57]
	v_pk_mul_f32 v[56:57], v[60:61], v[174:175] op_sel_hi:[0,1]
	v_pk_add_f32 v[190:191], s[46:47], v[56:57]
	v_pk_mul_f32 v[56:57], v[60:61], v[176:177] op_sel_hi:[0,1]
	v_pk_add_f32 v[192:193], s[46:47], v[56:57]
	v_pk_mul_f32 v[56:57], v[60:61], v[178:179] op_sel_hi:[0,1]
	v_pk_add_f32 v[194:195], s[46:47], v[56:57]
	v_add3_u32 v208, v180, v181, v182
	v_add3_u32 v208, v208, v183, v184
	v_add3_u32 v208, v208, v185, v186
	v_add3_u32 v208, v208, v187, v188
	v_add3_u32 v208, v208, v189, v190
	v_add3_u32 v208, v208, v191, v192
	v_add3_u32 v208, v208, v193, v194
	v_add_u32_e32 v208, v208, v195
	v_add_u32_e32 v208, 0x4bffff80, v208
; __device__ __forceinline__ void xn2_rows(const bf16* __restrict__ hb, const float* __restrict__ g, bf16* __restrict__ outp, unsigned char* __restrict__ xq, float* __restrict__ xs, int gwave, int nwaves, int lane, int rend) {
;     ...
;         const v4u* xb = (const v4u*)(hb + (size_t)row * D) + lane;
;         float v[2][8]; float ss = 0.f;
; #pragma unroll
;         for (int j = 0; j < 2; ++j) { const v4u w = xb[64 * j]; const unsigned ww[4] = {w.x, w.y, w.z, w.w};
; #pragma unroll
;             for (int e = 0; e < 4; ++e) { v[j][2 * e] = __uint_as_float(ww[e] << 16); v[j][2 * e + 1] = __uint_as_float(ww[e] & 0xffff0000u); ss += v[j][2 * e] * v[j][2 * e] + v[j][2 * e + 1] * v[j][2 * e + 1]; } }
;         ss = wave_sum(ss);
;         const float r = rsqrtf(ss * (1.f / D) + EPS);
;         float y[2][8]; float mx = 0.f;
; #pragma unroll
;         for (int j = 0; j < 2; ++j) { const float4 g0 = ((const float4*)g)[2 * lane + 128 * j], g1 = ((const float4*)g)[2 * lane + 128 * j + 1]; const float gg[8] = {g0.x, g0.y, g0.z, g0.w, g1.x, g1.y, g1.z, g1.w};
; #pragma unroll
;             for (int e = 0; e < 8; ++e) { y[j][e] = v[j][e] * r * gg[e]; mx = fmaxf(mx, fabsf(y[j][e])); }
;             v4u ow; ow.x = pk2(y[j][0], y[j][1]); ow.y = pk2(y[j][2], y[j][3]); ow.z = pk2(y[j][4], y[j][5]); ow.w = pk2(y[j][6], y[j][7]);
;             __builtin_amdgcn_raw_buffer_store_b128(ow, rsO, (int)(((unsigned)row * D + 8u * (unsigned)lane + 512u * j) * 2u), 0, 16); }
;         mx = wave_max_dpp(mx);
;         const float sc = mx > 0.f ? mx * (1.f / 119.f) : 1.f, inv = 1.f / sc;
;         int sx = 0; unsigned W[4];
; #pragma unroll
;         for (int j = 0; j < 2; ++j) { unsigned wh = 0u, wl = 0u;
; #pragma unroll
;             for (int e = 0; e < 8; ++e) { const int q = (int)rintf(y[j][e] * inv); sx += q; const unsigned tq = (unsigned)(q + 8);
;                 wl |= ((tq & 15u) ^ 8u) << (4 * e); wh |= (((unsigned)((int)tq >> 4)) & 15u) << (4 * e); }
;             W[j] = wh; W[2 + j] = wl; }
;         { const bool o1 = (lane & 1) != 0, o2 = (lane & 2) != 0;
; #pragma unroll
;           for (int p = 0; p < 4; p += 2) { const unsigned t = o1 ? W[p] : W[p + 1]; const unsigned rc = (unsigned)__builtin_amdgcn_update_dpp(0, (int)t, 0xB1, 0xf, 0xf, false); if (o1) W[p] = rc; else W[p + 1] = rc; }
; #pragma unroll
	v_perm_b32 v204, v182, v180, s48
	v_perm_b32 v205, v186, v184, s48
	v_perm_b32 v196, v205, v204, s49
	v_perm_b32 v204, v183, v181, s48
	v_perm_b32 v205, v187, v185, s48
	v_perm_b32 v197, v205, v204, s49
	v_lshlrev_b32_e32 v204, 4, v197
	v_lshrrev_b32_e32 v205, 4, v196
	v_bfi_b32 v202, s45, v196, v204
	v_bfi_b32 v200, s45, v205, v197
	v_xor_b32_e32 v202, 0x88888888, v202
	v_perm_b32 v204, v190, v188, s48
	v_perm_b32 v205, v194, v192, s48
	v_perm_b32 v196, v205, v204, s49
	v_perm_b32 v204, v191, v189, s48
	v_perm_b32 v205, v195, v193, s48
	v_perm_b32 v197, v205, v204, s49
	v_lshlrev_b32_e32 v204, 4, v197
	v_lshrrev_b32_e32 v205, 4, v196
	v_bfi_b32 v203, s45, v196, v204
	v_bfi_b32 v201, s45, v205, v197
	v_xor_b32_e32 v203, 0x88888888, v203
	v_cndmask_b32_e64 v204, v200, v201, s[4:5]
	v_cndmask_b32_e64 v205, v202, v203, s[4:5]
	s_nop 1
	v_mov_b32_dpp v206, v204 quad_perm:[1,0,3,2] row_mask:0xf bank_mask:0xf
	v_mov_b32_dpp v207, v205 quad_perm:[1,0,3,2] row_mask:0xf bank_mask:0xf
	s_nop 0
	v_cndmask_b32_e64 v200, v206, v200, s[4:5]
	v_cndmask_b32_e64 v201, v201, v206, s[4:5]
	v_cndmask_b32_e64 v202, v207, v202, s[4:5]
	v_cndmask_b32_e64 v203, v203, v207, s[4:5]
	v_cndmask_b32_e64 v204, v200, v202, s[6:7]
	v_cndmask_b32_e64 v205, v201, v203, s[6:7]
	s_nop 1
	v_mov_b32_dpp v206, v204 quad_perm:[2,3,0,1] row_mask:0xf bank_mask:0xf
	v_mov_b32_dpp v207, v205 quad_perm:[2,3,0,1] row_mask:0xf bank_mask:0xf
	s_nop 0
	v_cndmask_b32_e64 v200, v206, v200, s[6:7]
	v_cndmask_b32_e64 v202, v202, v206, s[6:7]
	v_cndmask_b32_e64 v201, v207, v201, s[6:7]
	v_cndmask_b32_e64 v203, v203, v207, s[6:7]
	buffer_store_dwordx4 v[200:203], v211, s[16:19], 0 offen sc1
	v_add_u32_e32 v211, 0x1000, v211
	s_nop 1
	v_add_u32_dpp v208, v208, v208 quad_perm:[1,0,3,2] row_mask:0xf bank_mask:0xf bound_ctrl:1
	s_nop 1
	v_add_u32_dpp v208, v208, v208 quad_perm:[2,3,0,1] row_mask:0xf bank_mask:0xf bound_ctrl:1
	s_nop 1
	v_add_u32_dpp v208, v208, v208 row_half_mirror row_mask:0xf bank_mask:0xf bound_ctrl:1
	s_nop 1
	v_add_u32_dpp v208, v208, v208 row_mirror row_mask:0xf bank_mask:0xf bound_ctrl:1
	s_nop 1
	v_readlane_b32 s28, v208, 0
	v_readlane_b32 s29, v208, 16
	v_readlane_b32 s30, v208, 32
	v_readlane_b32 s31, v208, 48
	s_nop 1
	s_add_i32 s28, s29, s28
	s_add_i32 s28, s28, s30
	s_add_i32 s30, s28, s31
	s_and_saveexec_b64 s[24:25], s[8:9]
	v_mov_b32_e32 v70, s98
	v_mov_b32_e32 v71, s30
	ds_write_b32 v70, v59
	ds_write_b32 v70, v71 offset:256
	s_mov_b64 exec, s[24:25]
	s_add_i32 s98, s98, 32
	s_waitcnt vmcnt(8)
	v_lshlrev_b32_e32 v34, 16, v92
	v_and_b32_e32 v35, 0xffff0000, v92
	v_lshlrev_b32_e32 v36, 16, v93
	v_and_b32_e32 v37, 0xffff0000, v93
	v_lshlrev_b32_e32 v38, 16, v94
	v_and_b32_e32 v39, 0xffff0000, v94
	v_lshlrev_b32_e32 v40, 16, v95
	v_and_b32_e32 v41, 0xffff0000, v95
	v_lshlrev_b32_e32 v42, 16, v96
	v_and_b32_e32 v43, 0xffff0000, v96
	v_lshlrev_b32_e32 v44, 16, v97
	v_and_b32_e32 v45, 0xffff0000, v97
	v_lshlrev_b32_e32 v46, 16, v98
	v_and_b32_e32 v47, 0xffff0000, v98
	v_lshlrev_b32_e32 v48, 16, v99
	v_and_b32_e32 v49, 0xffff0000, v99
	v_lshl_add_u64 v[150:151], v[150:151], 0, s[100:101]
	global_load_dwordx4 v[92:95], v[150:151], off
	global_load_dwordx4 v[96:99], v[150:151], off offset:1024
	v_pk_mul_f32 v[50:51], v[34:35], v[34:35]
	v_pk_fma_f32 v[50:51], v[36:37], v[36:37], v[50:51]
	v_pk_fma_f32 v[50:51], v[38:39], v[38:39], v[50:51]
	v_pk_fma_f32 v[50:51], v[40:41], v[40:41], v[50:51]
	v_pk_fma_f32 v[50:51], v[42:43], v[42:43], v[50:51]
	v_pk_fma_f32 v[50:51], v[44:45], v[44:45], v[50:51]
	v_pk_fma_f32 v[50:51], v[46:47], v[46:47], v[50:51]
	v_pk_fma_f32 v[50:51], v[48:49], v[48:49], v[50:51]
	v_add_f32_e32 v52, v50, v51
	s_nop 1
	v_add_f32_dpp v52, v52, v52 quad_perm:[1,0,3,2] row_mask:0xf bank_mask:0xf bound_ctrl:1
	s_nop 1
	v_add_f32_dpp v52, v52, v52 quad_perm:[2,3,0,1] row_mask:0xf bank_mask:0xf bound_ctrl:1
	s_nop 1
	v_add_f32_dpp v52, v52, v52 row_half_mirror row_mask:0xf bank_mask:0xf bound_ctrl:1
	s_nop 1
	v_add_f32_dpp v52, v52, v52 row_mirror row_mask:0xf bank_mask:0xf bound_ctrl:1
	s_nop 1
	v_readlane_b32 s28, v52, 16
	v_readlane_b32 s29, v52, 48
	v_readlane_b32 s24, v52, 0
	v_readlane_b32 s25, v52, 32
	s_nop 1
	v_mov_b32_e32 v52, s28
	v_mov_b32_e32 v53, s29
	v_pk_add_f32 v[52:53], s[24:25], v[52:53]
	s_nop 0
	v_add_f32_e32 v52, v52, v53
	v_fmamk_f32 v52, v52, 0x3a800000, v29
	v_rsq_f32_e32 v54, v52
	s_nop 0
	v_pk_mul_f32 v[56:57], v[54:55], v[34:35] op_sel_hi:[0,1]
	v_pk_mul_f32 v[164:165], v[6:7], v[56:57]
	v_pk_mul_f32 v[56:57], v[54:55], v[36:37] op_sel_hi:[0,1]
	v_pk_mul_f32 v[166:167], v[8:9], v[56:57]
	v_pk_mul_f32 v[56:57], v[54:55], v[38:39] op_sel_hi:[0,1]
	v_pk_mul_f32 v[168:169], v[2:3], v[56:57]
	v_pk_mul_f32 v[56:57], v[54:55], v[40:41] op_sel_hi:[0,1]
	v_pk_mul_f32 v[170:171], v[4:5], v[56:57]
	v_pk_mul_f32 v[56:57], v[54:55], v[42:43] op_sel_hi:[0,1]
	v_pk_mul_f32 v[172:173], v[14:15], v[56:57]
	v_pk_mul_f32 v[56:57], v[54:55], v[44:45] op_sel_hi:[0,1]
	v_pk_mul_f32 v[174:175], v[16:17], v[56:57]
	v_pk_mul_f32 v[56:57], v[54:55], v[46:47] op_sel_hi:[0,1]
	v_pk_mul_f32 v[176:177], v[10:11], v[56:57]
	v_pk_mul_f32 v[56:57], v[54:55], v[48:49] op_sel_hi:[0,1]
	v_pk_mul_f32 v[178:179], v[12:13], v[56:57]
	v_max3_f32 v58, |v164|, 0, |v165|
	v_max3_f32 v58, v58, |v166|, |v167|
	v_max3_f32 v58, v58, |v168|, |v169|
	v_max3_f32 v58, v58, |v170|, |v171|
	v_max3_f32 v58, v58, |v172|, |v173|
	v_max3_f32 v58, v58, |v174|, |v175|
	v_max3_f32 v58, v58, |v176|, |v177|
	v_max3_f32 v58, v58, |v178|, |v179|
	v_cvt_pk_bf16_f32 v62, v164, v165
	v_cvt_pk_bf16_f32 v63, v166, v167
	v_cvt_pk_bf16_f32 v64, v168, v169
	v_cvt_pk_bf16_f32 v65, v170, v171
; __device__ __forceinline__ void xn2_rows(const bf16* __restrict__ hb, const float* __restrict__ g, bf16* __restrict__ outp, unsigned char* __restrict__ xq, float* __restrict__ xs, int gwave, int nwaves, int lane, int rend) {
;     ...
;             v4u ow; ow.x = pk2(y[j][0], y[j][1]); ow.y = pk2(y[j][2], y[j][3]); ow.z = pk2(y[j][4], y[j][5]); ow.w = pk2(y[j][6], y[j][7]);
;             __builtin_amdgcn_raw_buffer_store_b128(ow, rsO, (int)(((unsigned)row * D + 8u * (unsigned)lane + 512u * j) * 2u), 0, 16); }
;         mx = wave_max_dpp(mx);
;         const float sc = mx > 0.f ? mx * (1.f / 119.f) : 1.f, inv = 1.f / sc;
;         int sx = 0; unsigned W[4];
; #pragma unroll
;         for (int j = 0; j < 2; ++j) { unsigned wh = 0u, wl = 0u;
; #pragma unroll
;             for (int e = 0; e < 8; ++e) { const int q = (int)rintf(y[j][e] * inv); sx += q; const unsigned tq = (unsigned)(q + 8);
;                 wl |= ((tq & 15u) ^ 8u) << (4 * e); wh |= (((unsigned)((int)tq >> 4)) & 15u) << (4 * e); }
;             W[j] = wh; W[2 + j] = wl; }
;         { const bool o1 = (lane & 1) != 0, o2 = (lane & 2) != 0;
; #pragma unroll
;           for (int p = 0; p < 4; p += 2) { const unsigned t = o1 ? W[p] : W[p + 1]; const unsigned rc = (unsigned)__builtin_amdgcn_update_dpp(0, (int)t, 0xB1, 0xf, 0xf, false); if (o1) W[p] = rc; else W[p + 1] = rc; }
; #pragma unroll
;           for (int p = 0; p < 2; ++p) { const unsigned t = o2 ? W[p] : W[p + 2]; const unsigned rc = (unsigned)__builtin_amdgcn_update_dpp(0, (int)t, 0x4E, 0xf, 0xf, false); if (o2) W[p] = rc; else W[p + 2] = rc; } }
;         { const int m = lane & 3; v4u pw; pw.x = W[0]; pw.y = W[1]; pw.z = W[2]; pw.w = W[3];
;           __builtin_amdgcn_raw_buffer_store_b128(pw, rsQ, (int)((m & 2 ? 8u * (unsigned)MiB : 0u) + (unsigned)row * 512u + (unsigned)(m & 1) * 256u + 16u * (unsigned)(lane >> 2)), 0, 16); }
;         sx = wave_sum_dpp_i(sx);
;         if (lane == 0) { __hip_atomic_store(xs + row, sc, __ATOMIC_RELAXED, __HIP_MEMORY_SCOPE_AGENT); __hip_atomic_store((int*)(xs + T) + row, sx, __ATOMIC_RELAXED, __HIP_MEMORY_SCOPE_AGENT); }
	v_cvt_pk_bf16_f32 v66, v172, v173
	v_cvt_pk_bf16_f32 v67, v174, v175
	v_cvt_pk_bf16_f32 v68, v176, v177
	v_cvt_pk_bf16_f32 v69, v178, v179
	buffer_store_dwordx4 v[62:65], v210, s[12:15], 0 offen
	buffer_store_dwordx4 v[66:69], v210, s[12:15], 0 offen offset:1024
	v_add_u32_e32 v210, 0x4000, v210
	s_nop 1
	v_max_f32_dpp v58, v58, v58 quad_perm:[1,0,3,2] row_mask:0xf bank_mask:0xf
	s_nop 1
	v_max_f32_dpp v58, v58, v58 quad_perm:[2,3,0,1] row_mask:0xf bank_mask:0xf
	s_nop 1
	v_max_f32_dpp v58, v58, v58 row_half_mirror row_mask:0xf bank_mask:0xf
	s_nop 1
	v_max_f32_dpp v58, v58, v58 row_mirror row_mask:0xf bank_mask:0xf
	s_nop 1
	v_readlane_b32 s28, v58, 32
	v_readlane_b32 s29, v58, 48
	v_readlane_b32 s24, v58, 0
	v_readlane_b32 s25, v58, 16
	s_nop 1
	v_mov_b32_e32 v59, s29
	v_max_f32_e32 v59, s28, v59
	v_mov_b32_e32 v70, s25
	v_max3_f32 v59, s24, v70, v59
	v_mul_f32_e32 v70, 0x3c09ae41, v59
	v_cmp_lt_f32_e32 vcc, 0, v59
	s_nop 1
	v_cndmask_b32_e32 v59, 1.0, v70, vcc
	v_div_scale_f32 v70, s[24:25], v59, v59, 1.0
	v_rcp_f32_e32 v71, v70
	v_div_scale_f32 v72, vcc, 1.0, v59, 1.0
	v_fma_f32 v73, -v70, v71, 1.0
	v_fmac_f32_e32 v71, v73, v71
	v_mul_f32_e32 v73, v72, v71
	v_fma_f32 v74, -v70, v73, v72
	v_fmac_f32_e32 v73, v74, v71
	v_fma_f32 v70, -v70, v73, v72
	v_div_fmas_f32 v70, v70, v71, v73
	v_div_fixup_f32 v60, v70, v59, 1.0
	v_pk_mul_f32 v[56:57], v[60:61], v[164:165] op_sel_hi:[0,1]
	v_pk_add_f32 v[180:181], s[46:47], v[56:57]
	v_pk_mul_f32 v[56:57], v[60:61], v[166:167] op_sel_hi:[0,1]
	v_pk_add_f32 v[182:183], s[46:47], v[56:57]
	v_pk_mul_f32 v[56:57], v[60:61], v[168:169] op_sel_hi:[0,1]
	v_pk_add_f32 v[184:185], s[46:47], v[56:57]
	v_pk_mul_f32 v[56:57], v[60:61], v[170:171] op_sel_hi:[0,1]
	v_pk_add_f32 v[186:187], s[46:47], v[56:57]
	v_pk_mul_f32 v[56:57], v[60:61], v[172:173] op_sel_hi:[0,1]
	v_pk_add_f32 v[188:189], s[46:47], v[56:57]
	v_pk_mul_f32 v[56:57], v[60:61], v[174:175] op_sel_hi:[0,1]
	v_pk_add_f32 v[190:191], s[46:47], v[56:57]
	v_pk_mul_f32 v[56:57], v[60:61], v[176:177] op_sel_hi:[0,1]
	v_pk_add_f32 v[192:193], s[46:47], v[56:57]
	v_pk_mul_f32 v[56:57], v[60:61], v[178:179] op_sel_hi:[0,1]
	v_pk_add_f32 v[194:195], s[46:47], v[56:57]
	v_add3_u32 v208, v180, v181, v182
	v_add3_u32 v208, v208, v183, v184
	v_add3_u32 v208, v208, v185, v186
	v_add3_u32 v208, v208, v187, v188
	v_add3_u32 v208, v208, v189, v190
	v_add3_u32 v208, v208, v191, v192
	v_add3_u32 v208, v208, v193, v194
	v_add_u32_e32 v208, v208, v195
	v_add_u32_e32 v208, 0x4bffff80, v208
	v_perm_b32 v204, v182, v180, s48
	v_perm_b32 v205, v186, v184, s48
	v_perm_b32 v196, v205, v204, s49
	v_perm_b32 v204, v183, v181, s48
	v_perm_b32 v205, v187, v185, s48
	v_perm_b32 v197, v205, v204, s49
	v_lshlrev_b32_e32 v204, 4, v197
	v_lshrrev_b32_e32 v205, 4, v196
	v_bfi_b32 v202, s45, v196, v204
	v_bfi_b32 v200, s45, v205, v197
	v_xor_b32_e32 v202, 0x88888888, v202
	v_perm_b32 v204, v190, v188, s48
	v_perm_b32 v205, v194, v192, s48
	v_perm_b32 v196, v205, v204, s49
	v_perm_b32 v204, v191, v189, s48
	v_perm_b32 v205, v195, v193, s48
	v_perm_b32 v197, v205, v204, s49
	v_lshlrev_b32_e32 v204, 4, v197
	v_lshrrev_b32_e32 v205, 4, v196
	v_bfi_b32 v203, s45, v196, v204
	v_bfi_b32 v201, s45, v205, v197
	v_xor_b32_e32 v203, 0x88888888, v203
	v_cndmask_b32_e64 v204, v200, v201, s[4:5]
	v_cndmask_b32_e64 v205, v202, v203, s[4:5]
	s_nop 1
	v_mov_b32_dpp v206, v204 quad_perm:[1,0,3,2] row_mask:0xf bank_mask:0xf
	v_mov_b32_dpp v207, v205 quad_perm:[1,0,3,2] row_mask:0xf bank_mask:0xf
	s_nop 0
	v_cndmask_b32_e64 v200, v206, v200, s[4:5]
	v_cndmask_b32_e64 v201, v201, v206, s[4:5]
	v_cndmask_b32_e64 v202, v207, v202, s[4:5]
	v_cndmask_b32_e64 v203, v203, v207, s[4:5]
	v_cndmask_b32_e64 v204, v200, v202, s[6:7]
	v_cndmask_b32_e64 v205, v201, v203, s[6:7]
	s_nop 1
	v_mov_b32_dpp v206, v204 quad_perm:[2,3,0,1] row_mask:0xf bank_mask:0xf
	v_mov_b32_dpp v207, v205 quad_perm:[2,3,0,1] row_mask:0xf bank_mask:0xf
	s_nop 0
	v_cndmask_b32_e64 v200, v206, v200, s[6:7]
	v_cndmask_b32_e64 v202, v202, v206, s[6:7]
	v_cndmask_b32_e64 v201, v207, v201, s[6:7]
	v_cndmask_b32_e64 v203, v203, v207, s[6:7]
	buffer_store_dwordx4 v[200:203], v211, s[16:19], 0 offen sc1
	v_add_u32_e32 v211, 0x1000, v211
	s_nop 1
	v_add_u32_dpp v208, v208, v208 quad_perm:[1,0,3,2] row_mask:0xf bank_mask:0xf bound_ctrl:1
	s_nop 1
	v_add_u32_dpp v208, v208, v208 quad_perm:[2,3,0,1] row_mask:0xf bank_mask:0xf bound_ctrl:1
	s_nop 1
	v_add_u32_dpp v208, v208, v208 row_half_mirror row_mask:0xf bank_mask:0xf bound_ctrl:1
	s_nop 1
	v_add_u32_dpp v208, v208, v208 row_mirror row_mask:0xf bank_mask:0xf bound_ctrl:1
	s_nop 1
	v_readlane_b32 s28, v208, 0
	v_readlane_b32 s29, v208, 16
	v_readlane_b32 s30, v208, 32
	v_readlane_b32 s31, v208, 48
	s_nop 1
	s_add_i32 s28, s29, s28
	s_add_i32 s28, s28, s30
	s_add_i32 s30, s28, s31
	s_and_saveexec_b64 s[24:25], s[8:9]
	v_mov_b32_e32 v70, s98
	v_mov_b32_e32 v71, s30
	ds_write_b32 v70, v59
	ds_write_b32 v70, v71 offset:256
	s_mov_b64 exec, s[24:25]
	s_add_i32 s98, s98, 32
	s_add_i32 s32, s32, 1
	s_cmp_eq_u32 s32, 3
	s_cselect_b32 s100, 0, s100
	s_cmp_lg_u32 s32, 4
	s_cbranch_scc1 .Lp8_trip
	s_waitcnt lgkmcnt(0)
	s_barrier
	s_cmp_lg_u32 s95, 0
	s_cbranch_scc1 .Lp8_xs_done
	v_lshrrev_b32_e32 v70, 2, v18
	ds_read_b32 v71, v70
	ds_read_b32 v72, v70 offset:256
	s_lshl_b32 s10, s42, 6
	s_lshl_b32 s11, s43, 8
	s_add_i32 s24, s10, s11
	s_lshl_b32 s24, s24, 2
	s_add_u32 s28, s90, s24
	s_addc_u32 s29, s91, 0
	v_add_u32_e32 v73, v30, v70
	v_add_u32_e32 v74, v31, v70
	s_waitcnt lgkmcnt(0)
	global_store_dword v73, v71, s[28:29] sc1
	global_store_dword v74, v72, s[28:29] sc1
